# adds P5 epilogue: x1b residual loads issued linearly (1 KiB contiguous per wave-load) and transposed to the MFMA layout through the LDS scratch one step ahead
# baseline (speedup 1.0000x reference)
; __host__ __device__ __forceinline__ size_t img_off(int row, int col, int nkt) { return ((size_t)((row >> 7) * nkt + (col >> 6)) << 14) + (size_t)lds_byte(row & 127, col & 63); }
;     __device__ __forceinline__ void operator()(const f32x4 (&acc)[2][2][4][2], const Unit& u, int wr, int wc, int fr, int fq) const {
;     ...
;                 for (int bj = 0; bj < 2; ++bj) { const u32x4 xb = __builtin_nontemporal_load((const u32x4*)(x1b + img_off(row, col0 + bj * HALF, 16))); float* p = y + off + bj * HALF;
;                     const f32x4 x0 = (f32x4){__builtin_bit_cast(float, xb.x << 16), __builtin_bit_cast(float, xb.x & 0xffff0000u), __builtin_bit_cast(float, xb.y << 16), __builtin_bit_cast(float, xb.y & 0xffff0000u)};
;                     const f32x4 x1 = (f32x4){__builtin_bit_cast(float, xb.z << 16), __builtin_bit_cast(float, xb.z & 0xffff0000u), __builtin_bit_cast(float, xb.w << 16), __builtin_bit_cast(float, xb.w & 0xffff0000u)};
;                     __builtin_nontemporal_store(acc[ai][bj][m][0] + x0, (f32x4*)p); __builtin_nontemporal_store(acc[ai][bj][m][1] + x1, (f32x4*)(p + 4)); } }
.LBB0_1427:
	s_lshl_b32 s13, s56, 8
	s_lshl_b32 s12, s55, 8
	s_or_b32 s13, s13, s45
	s_add_i32 s12, s12, s44
	v_or_b32_e32 v138, s13, v141
	v_or_b32_e32 v136, s12, v140
	v_lshlrev_b32_e32 v130, 1, v138
	s_bfe_u32 s55, s45, 0x10005
	v_and_b32_e32 v146, 48, v130
	s_ashr_i32 s12, s12, 3
	v_lshlrev_b32_e32 v130, 6, v136
	s_and_b32 s36, s12, -16
	s_ashr_i32 s57, s13, 6
	s_or_b32 s37, s55, s49
	v_and_or_b32 v147, v130, s48, v146
	v_lshlrev_b32_e32 v130, 2, v136
	s_add_i32 s12, s36, s57
	s_lshl_b32 s58, s37, 10
	v_and_b32_e32 v160, 32, v130
	s_ashr_i32 s13, s12, 31
	v_bitop3_b32 v130, v147, s58, v160 bitop3:0xde
	s_lshl_b64 s[12:13], s[12:13], 14
	v_lshl_add_u64 v[152:153], s[30:31], 0, v[130:131]
	v_lshl_add_u64 v[148:149], v[152:153], 0, s[12:13]
	s_nop 0
	v_readfirstlane_b32 s98, v148
	v_readfirstlane_b32 s99, v149
	v_lshlrev_b32_e32 v244, 4, v200
	v_mov_b32_e32 v245, 0
	v_lshl_add_u64 v[148:149], s[98:99], 0, v[244:245]
	s_mov_b64 s[98:99], 0x1000
	s_mov_b64 s[100:101], 0x8000
	v_lshl_add_u64 v[230:231], v[148:149], 0, s[98:99]
	v_lshl_add_u64 v[232:233], v[148:149], 0, s[100:101]
	v_lshl_add_u64 v[234:235], v[230:231], 0, s[100:101]
	s_mov_b64 s[100:101], 0x40000
	v_lshl_add_u64 v[236:237], v[148:149], 0, s[100:101]
	v_lshl_add_u64 v[238:239], v[230:231], 0, s[100:101]
	v_lshl_add_u64 v[240:241], v[232:233], 0, s[100:101]
	v_lshl_add_u64 v[242:243], v[234:235], 0, s[100:101]
	global_load_dwordx4 v[162:165], v[148:149], off nt
	global_load_dwordx4 v[166:169], v[232:233], off nt
	global_load_dwordx4 v[170:173], v[148:149], off offset:2048 nt
	global_load_dwordx4 v[174:177], v[232:233], off offset:2048 nt
	global_load_dwordx4 v[178:181], v[230:231], off nt
	global_load_dwordx4 v[182:185], v[234:235], off nt
	global_load_dwordx4 v[186:189], v[230:231], off offset:2048 nt
	global_load_dwordx4 v[190:193], v[234:235], off offset:2048 nt
	global_load_dwordx4 v[194:197], v[236:237], off nt
	global_load_dwordx4 v[202:205], v[240:241], off nt
	global_load_dwordx4 v[206:209], v[236:237], off offset:2048 nt
	global_load_dwordx4 v[210:213], v[240:241], off offset:2048 nt
	global_load_dwordx4 v[214:217], v[238:239], off nt
	global_load_dwordx4 v[218:221], v[242:243], off nt
	global_load_dwordx4 v[222:225], v[238:239], off offset:2048 nt
	global_load_dwordx4 v[226:229], v[242:243], off offset:2048 nt
	s_lshl_b32 s98, s44, 7
	s_lshl_b32 s99, s45, 6
	s_add_i32 s98, s98, s99
	s_add_i32 s98, s98, 0x24000
	v_and_b32_e32 v244, 15, v200
	v_lshrrev_b32_e32 v245, 4, v200
	v_and_b32_e32 v246, 3, v244
	v_xor_b32_e32 v246, v245, v246
	v_lshlrev_b32_e32 v246, 5, v246
	v_lshl_add_u32 v246, v244, 7, v246
	v_add_u32_e32 v248, s98, v246
	v_lshrrev_b32_e32 v244, 3, v200
	v_and_b32_e32 v245, 7, v200
	v_lshlrev_b32_e32 v161, 4, v245
	v_lshl_add_u32 v161, v244, 12, v161
	v_add_u32_e32 v201, 0x8000, v161
	v_lshrrev_b32_e32 v246, 1, v245
	v_and_b32_e32 v245, 1, v245
	v_and_b32_e32 v247, 3, v244
	v_xor_b32_e32 v246, v246, v247
	v_lshl_or_b32 v246, v246, 1, v245
	v_lshlrev_b32_e32 v246, 4, v246
	v_lshl_add_u32 v246, v244, 7, v246
	v_add_u32_e32 v249, s98, v246
	v_and_b32_e32 v244, 15, v200
	v_lshrrev_b32_e32 v245, 4, v200
	v_and_b32_e32 v246, 3, v244
	v_xor_b32_e32 v246, v245, v246
	v_lshlrev_b32_e32 v246, 4, v246
	v_lshl_add_u32 v246, v244, 6, v246
	v_add_u32_e32 v230, s98, v246
	v_lshrrev_b32_e32 v244, 2, v200
	v_lshrrev_b32_e32 v245, 5, v200
	v_and_b32_e32 v246, 3, v200
	v_lshlrev_b32_e32 v245, 1, v245
	v_xor_b32_e32 v246, v246, v245
	v_and_b32_e32 v245, 3, v244
	v_xor_b32_e32 v246, v246, v245
	v_lshlrev_b32_e32 v246, 4, v246
	v_lshl_add_u32 v246, v244, 6, v246
	v_add_u32_e32 v231, s98, v246
	s_waitcnt vmcnt(14)
	ds_write_b128 v231, v[162:165]
	ds_read_b128 v[162:165], v230
	v_readlane_b32 s60, v251, 6
	v_ashrrev_i32_e32 v137, 31, v136
	s_or_b32 s56, s57, 2
	v_readlane_b32 s62, v251, 8
	v_readlane_b32 s63, v251, 9
	v_readlane_b32 s66, v251, 12
	v_readlane_b32 s67, v251, 13
	v_ashrrev_i32_e32 v139, 31, v138
	v_lshlrev_b64 v[154:155], 12, v[136:137]
	s_add_i32 s36, s36, s56
	s_mov_b64 s[62:63], s[66:67]
	v_lshlrev_b64 v[138:139], 2, v[138:139]
	v_lshl_add_u64 v[154:155], s[62:63], 0, v[154:155]
	s_ashr_i32 s37, s36, 31
	v_lshl_add_u64 v[154:155], v[154:155], 0, v[138:139]
	s_lshl_b64 s[36:37], s[36:37], 14
	v_lshl_add_u64 v[152:153], v[152:153], 0, s[36:37]
	s_and_b64 vcc, exec, s[0:1]
	s_mov_b64 s[0:1], -1
	v_readlane_b32 s61, v251, 7
	v_readlane_b32 s64, v251, 10
	v_readlane_b32 s65, v251, 11
	s_waitcnt vmcnt(14)
	ds_write_b128 v231, v[166:169]
	ds_read_b128 v[166:169], v230
	s_waitcnt lgkmcnt(2)
	v_lshlrev_b32_e32 v156, 16, v162
	v_and_b32_e32 v157, 0xffff0000, v162
	v_lshlrev_b32_e32 v148, 16, v163
	v_and_b32_e32 v149, 0xffff0000, v163
	v_lshlrev_b32_e32 v158, 16, v164
	v_and_b32_e32 v159, 0xffff0000, v164
	v_lshlrev_b32_e32 v150, 16, v165
	v_and_b32_e32 v151, 0xffff0000, v165
	v_pk_add_f32 v[126:127], v[126:127], v[148:149]
	v_pk_add_f32 v[124:125], v[124:125], v[156:157]
	v_pk_add_f32 v[122:123], v[122:123], v[150:151]
	v_pk_add_f32 v[120:121], v[120:121], v[158:159]
	s_nop 0
	v_readfirstlane_b32 s98, v154
	v_readfirstlane_b32 s99, v155
	ds_write_b128 v248, v[124:127]
	ds_write_b128 v248, v[120:123] offset:16
	ds_read_b128 v[232:235], v249
	ds_read_b128 v[236:239], v249 offset:1024
	s_nop 0
	v_or_b32_e32 v124, 16, v136
	v_lshrrev_b32_e32 v125, 3, v124
	v_and_or_b32 v125, v125, 10, s55
	v_lshlrev_b32_e32 v125, 10, v125
	v_bitop3_b32 v130, v147, v125, v160 bitop3:0xde
	v_lshl_add_u64 v[126:127], s[30:31], 0, v[130:131]
	v_lshl_add_u64 v[148:149], v[126:127], 0, s[12:13]
	v_ashrrev_i32_e32 v125, 31, v124
	s_waitcnt vmcnt(13)
	ds_write_b128 v231, v[170:173]
	ds_read_b128 v[170:173], v230
	s_waitcnt lgkmcnt(6)
; __host__ __device__ __forceinline__ size_t img_off(int row, int col, int nkt) { return ((size_t)((row >> 7) * nkt + (col >> 6)) << 14) + (size_t)lds_byte(row & 127, col & 63); }
;     __device__ __forceinline__ void operator()(const f32x4 (&acc)[2][2][4][2], const Unit& u, int wr, int wc, int fr, int fq) const {
;     ...
;                 for (int bj = 0; bj < 2; ++bj) { const u32x4 xb = __builtin_nontemporal_load((const u32x4*)(x1b + img_off(row, col0 + bj * HALF, 16))); float* p = y + off + bj * HALF;
;                     const f32x4 x0 = (f32x4){__builtin_bit_cast(float, xb.x << 16), __builtin_bit_cast(float, xb.x & 0xffff0000u), __builtin_bit_cast(float, xb.y << 16), __builtin_bit_cast(float, xb.y & 0xffff0000u)};
;                     const f32x4 x1 = (f32x4){__builtin_bit_cast(float, xb.z << 16), __builtin_bit_cast(float, xb.z & 0xffff0000u), __builtin_bit_cast(float, xb.w << 16), __builtin_bit_cast(float, xb.w & 0xffff0000u)};
;                     __builtin_nontemporal_store(acc[ai][bj][m][0] + x0, (f32x4*)p); __builtin_nontemporal_store(acc[ai][bj][m][1] + x1, (f32x4*)(p + 4)); } }
	v_lshlrev_b32_e32 v150, 16, v166
	v_and_b32_e32 v151, 0xffff0000, v166
	v_lshlrev_b32_e32 v120, 16, v167
	v_and_b32_e32 v121, 0xffff0000, v167
	v_lshlrev_b32_e32 v152, 16, v168
	v_and_b32_e32 v153, 0xffff0000, v168
	v_lshlrev_b32_e32 v122, 16, v169
	v_and_b32_e32 v123, 0xffff0000, v169
	v_pk_add_f32 v[118:119], v[118:119], v[120:121]
	v_pk_add_f32 v[116:117], v[116:117], v[150:151]
	v_pk_add_f32 v[114:115], v[114:115], v[122:123]
	v_pk_add_f32 v[112:113], v[112:113], v[152:153]
	ds_write_b128 v248, v[116:119]
	ds_write_b128 v248, v[112:115] offset:16
	ds_read_b128 v[240:243], v249
	ds_read_b128 v[244:247], v249 offset:1024
	s_waitcnt lgkmcnt(6)
	global_store_dwordx4 v161, v[232:235], s[98:99] nt
	global_store_dwordx4 v201, v[236:239], s[98:99] nt
	s_nop 0
	v_lshlrev_b64 v[116:117], 12, v[124:125]
	v_lshl_add_u64 v[116:117], s[62:63], 0, v[116:117]
	v_lshl_add_u64 v[116:117], v[116:117], 0, v[138:139]
	v_lshl_add_u64 v[118:119], v[126:127], 0, s[36:37]
	s_waitcnt vmcnt(14)
	ds_write_b128 v231, v[174:177]
	ds_read_b128 v[174:177], v230
	s_waitcnt lgkmcnt(6)
	v_lshlrev_b32_e32 v120, 16, v170
	v_and_b32_e32 v121, 0xffff0000, v170
	v_lshlrev_b32_e32 v112, 16, v171
	v_and_b32_e32 v113, 0xffff0000, v171
	v_lshlrev_b32_e32 v122, 16, v172
	v_and_b32_e32 v123, 0xffff0000, v172
	v_lshlrev_b32_e32 v114, 16, v173
	v_and_b32_e32 v115, 0xffff0000, v173
	v_pk_add_f32 v[110:111], v[110:111], v[112:113]
	v_pk_add_f32 v[108:109], v[108:109], v[120:121]
	v_pk_add_f32 v[106:107], v[106:107], v[114:115]
	v_pk_add_f32 v[104:105], v[104:105], v[122:123]
	s_nop 0
	v_readfirstlane_b32 s100, v116
	v_readfirstlane_b32 s101, v117
	ds_write_b128 v248, v[108:111]
	ds_write_b128 v248, v[104:107] offset:16
	ds_read_b128 v[232:235], v249
	ds_read_b128 v[236:239], v249 offset:1024
	s_waitcnt lgkmcnt(6)
	global_store_dwordx4 v161, v[240:243], s[98:99] offset:512 nt
	global_store_dwordx4 v201, v[244:247], s[98:99] offset:512 nt
	s_nop 0
	v_or_b32_e32 v108, 32, v136
	v_lshrrev_b32_e32 v109, 3, v108
	v_and_or_b32 v109, v109, 12, s55
	v_lshlrev_b32_e32 v109, 10, v109
	v_bitop3_b32 v130, v147, v109, v160 bitop3:0xde
	v_lshl_add_u64 v[110:111], s[30:31], 0, v[130:131]
	v_lshl_add_u64 v[112:113], v[110:111], 0, s[12:13]
	v_ashrrev_i32_e32 v109, 31, v108
	s_waitcnt vmcnt(15)
	ds_write_b128 v231, v[178:181]
	ds_read_b128 v[178:181], v230
	s_waitcnt lgkmcnt(6)
	v_lshlrev_b32_e32 v114, 16, v174
	v_and_b32_e32 v115, 0xffff0000, v174
	v_lshlrev_b32_e32 v104, 16, v175
	v_and_b32_e32 v105, 0xffff0000, v175
	v_lshlrev_b32_e32 v118, 16, v176
	v_and_b32_e32 v119, 0xffff0000, v176
	v_lshlrev_b32_e32 v106, 16, v177
	v_and_b32_e32 v107, 0xffff0000, v177
	v_pk_add_f32 v[102:103], v[102:103], v[104:105]
	v_pk_add_f32 v[100:101], v[100:101], v[114:115]
	v_pk_add_f32 v[98:99], v[98:99], v[106:107]
	v_pk_add_f32 v[96:97], v[96:97], v[118:119]
	ds_write_b128 v248, v[100:103]
	ds_write_b128 v248, v[96:99] offset:16
	ds_read_b128 v[240:243], v249
	ds_read_b128 v[244:247], v249 offset:1024
	s_waitcnt lgkmcnt(6)
	global_store_dwordx4 v161, v[232:235], s[100:101] nt
	global_store_dwordx4 v201, v[236:239], s[100:101] nt
	s_nop 0
	v_lshlrev_b64 v[100:101], 12, v[108:109]
	v_lshl_add_u64 v[100:101], s[62:63], 0, v[100:101]
	v_lshl_add_u64 v[100:101], v[100:101], 0, v[138:139]
	v_lshl_add_u64 v[102:103], v[110:111], 0, s[36:37]
	s_waitcnt vmcnt(16)
	ds_write_b128 v231, v[182:185]
	ds_read_b128 v[182:185], v230
	s_waitcnt lgkmcnt(6)
	v_lshlrev_b32_e32 v104, 16, v178
	v_and_b32_e32 v105, 0xffff0000, v178
	v_lshlrev_b32_e32 v96, 16, v179
	v_and_b32_e32 v97, 0xffff0000, v179
	v_lshlrev_b32_e32 v106, 16, v180
	v_and_b32_e32 v107, 0xffff0000, v180
	v_lshlrev_b32_e32 v98, 16, v181
	v_and_b32_e32 v99, 0xffff0000, v181
	v_pk_add_f32 v[94:95], v[94:95], v[96:97]
	v_pk_add_f32 v[92:93], v[92:93], v[104:105]
	v_pk_add_f32 v[90:91], v[90:91], v[98:99]
	v_pk_add_f32 v[88:89], v[88:89], v[106:107]
	s_nop 0
	v_readfirstlane_b32 s98, v100
	v_readfirstlane_b32 s99, v101
	ds_write_b128 v248, v[92:95]
	ds_write_b128 v248, v[88:91] offset:16
	ds_read_b128 v[232:235], v249
	ds_read_b128 v[236:239], v249 offset:1024
	s_waitcnt lgkmcnt(6)
	global_store_dwordx4 v161, v[240:243], s[100:101] offset:512 nt
	global_store_dwordx4 v201, v[244:247], s[100:101] offset:512 nt
	s_nop 0
	v_or_b32_e32 v92, 48, v136
	v_lshrrev_b32_e32 v93, 3, v92
	v_and_or_b32 v93, v93, 14, s55
	v_lshlrev_b32_e32 v93, 10, v93
	v_bitop3_b32 v130, v147, v93, v160 bitop3:0xde
	v_lshl_add_u64 v[94:95], s[30:31], 0, v[130:131]
	v_lshl_add_u64 v[96:97], v[94:95], 0, s[12:13]
	v_ashrrev_i32_e32 v93, 31, v92
	s_waitcnt vmcnt(17)
	ds_write_b128 v231, v[186:189]
	ds_read_b128 v[186:189], v230
	s_waitcnt lgkmcnt(6)
	v_lshlrev_b32_e32 v98, 16, v182
	v_and_b32_e32 v99, 0xffff0000, v182
	v_lshlrev_b32_e32 v88, 16, v183
	v_and_b32_e32 v89, 0xffff0000, v183
	v_lshlrev_b32_e32 v102, 16, v184
	v_and_b32_e32 v103, 0xffff0000, v184
	v_lshlrev_b32_e32 v90, 16, v185
	v_and_b32_e32 v91, 0xffff0000, v185
	v_pk_add_f32 v[86:87], v[86:87], v[88:89]
	v_pk_add_f32 v[84:85], v[84:85], v[98:99]
	v_pk_add_f32 v[82:83], v[82:83], v[90:91]
	v_pk_add_f32 v[80:81], v[80:81], v[102:103]
	ds_write_b128 v248, v[84:87]
	ds_write_b128 v248, v[80:83] offset:16
	ds_read_b128 v[240:243], v249
	ds_read_b128 v[244:247], v249 offset:1024
	s_waitcnt lgkmcnt(6)
	global_store_dwordx4 v161, v[232:235], s[98:99] nt
	global_store_dwordx4 v201, v[236:239], s[98:99] nt
	s_nop 0
	v_lshlrev_b64 v[84:85], 12, v[92:93]
	v_lshl_add_u64 v[84:85], s[62:63], 0, v[84:85]
	v_lshl_add_u64 v[84:85], v[84:85], 0, v[138:139]
	v_lshl_add_u64 v[86:87], v[94:95], 0, s[36:37]
	s_waitcnt vmcnt(18)
; __host__ __device__ __forceinline__ size_t img_off(int row, int col, int nkt) { return ((size_t)((row >> 7) * nkt + (col >> 6)) << 14) + (size_t)lds_byte(row & 127, col & 63); }
;     __device__ __forceinline__ void operator()(const f32x4 (&acc)[2][2][4][2], const Unit& u, int wr, int wc, int fr, int fq) const {
;     ...
;                 for (int bj = 0; bj < 2; ++bj) { const u32x4 xb = __builtin_nontemporal_load((const u32x4*)(x1b + img_off(row, col0 + bj * HALF, 16))); float* p = y + off + bj * HALF;
;                     const f32x4 x0 = (f32x4){__builtin_bit_cast(float, xb.x << 16), __builtin_bit_cast(float, xb.x & 0xffff0000u), __builtin_bit_cast(float, xb.y << 16), __builtin_bit_cast(float, xb.y & 0xffff0000u)};
;                     const f32x4 x1 = (f32x4){__builtin_bit_cast(float, xb.z << 16), __builtin_bit_cast(float, xb.z & 0xffff0000u), __builtin_bit_cast(float, xb.w << 16), __builtin_bit_cast(float, xb.w & 0xffff0000u)};
;                     __builtin_nontemporal_store(acc[ai][bj][m][0] + x0, (f32x4*)p); __builtin_nontemporal_store(acc[ai][bj][m][1] + x1, (f32x4*)(p + 4)); } }
	ds_write_b128 v231, v[190:193]
	ds_read_b128 v[190:193], v230
	s_waitcnt lgkmcnt(6)
	v_lshlrev_b32_e32 v88, 16, v186
	v_and_b32_e32 v89, 0xffff0000, v186
	v_lshlrev_b32_e32 v80, 16, v187
	v_and_b32_e32 v81, 0xffff0000, v187
	v_lshlrev_b32_e32 v90, 16, v188
	v_and_b32_e32 v91, 0xffff0000, v188
	v_lshlrev_b32_e32 v82, 16, v189
	v_and_b32_e32 v83, 0xffff0000, v189
	v_pk_add_f32 v[78:79], v[78:79], v[80:81]
	v_pk_add_f32 v[76:77], v[76:77], v[88:89]
	v_pk_add_f32 v[74:75], v[74:75], v[82:83]
	v_pk_add_f32 v[72:73], v[72:73], v[90:91]
	s_nop 0
	v_readfirstlane_b32 s100, v84
	v_readfirstlane_b32 s101, v85
	ds_write_b128 v248, v[76:79]
	ds_write_b128 v248, v[72:75] offset:16
	ds_read_b128 v[232:235], v249
	ds_read_b128 v[236:239], v249 offset:1024
	s_waitcnt lgkmcnt(6)
	global_store_dwordx4 v161, v[240:243], s[98:99] offset:512 nt
	global_store_dwordx4 v201, v[244:247], s[98:99] offset:512 nt
	s_nop 0
	v_add_u32_e32 v78, 0x80, v136
	v_ashrrev_i32_e32 v72, 3, v78
	v_lshlrev_b32_e32 v73, 6, v78
	v_lshlrev_b32_e32 v79, 2, v78
	v_and_b32_e32 v90, -16, v72
	v_and_or_b32 v80, v73, s48, v146
	v_and_b32_e32 v79, 32, v79
	v_add_u32_e32 v72, s57, v90
	v_ashrrev_i32_e32 v73, 31, v72
	v_bitop3_b32 v130, v80, s58, v79 bitop3:0xde
	v_lshlrev_b64 v[72:73], 14, v[72:73]
	v_lshl_add_u64 v[80:81], s[30:31], 0, v[130:131]
	v_lshl_add_u64 v[82:83], v[80:81], 0, v[72:73]
	v_ashrrev_i32_e32 v79, 31, v78
	s_waitcnt vmcnt(19)
	ds_write_b128 v231, v[194:197]
	ds_read_b128 v[194:197], v230
	s_waitcnt lgkmcnt(6)
	v_lshlrev_b32_e32 v86, 16, v190
	v_and_b32_e32 v87, 0xffff0000, v190
	v_lshlrev_b32_e32 v74, 16, v191
	v_and_b32_e32 v75, 0xffff0000, v191
	v_lshlrev_b32_e32 v88, 16, v192
	v_and_b32_e32 v89, 0xffff0000, v192
	v_lshlrev_b32_e32 v76, 16, v193
	v_and_b32_e32 v77, 0xffff0000, v193
	v_pk_add_f32 v[70:71], v[70:71], v[74:75]
	v_pk_add_f32 v[68:69], v[68:69], v[86:87]
	v_pk_add_f32 v[66:67], v[66:67], v[76:77]
	v_pk_add_f32 v[64:65], v[64:65], v[88:89]
	ds_write_b128 v248, v[68:71]
	ds_write_b128 v248, v[64:67] offset:16
	ds_read_b128 v[240:243], v249
	ds_read_b128 v[244:247], v249 offset:1024
	s_waitcnt lgkmcnt(6)
	global_store_dwordx4 v161, v[232:235], s[100:101] nt
	global_store_dwordx4 v201, v[236:239], s[100:101] nt
	s_nop 0
	v_add_u32_e32 v70, s56, v90
	v_lshlrev_b64 v[64:65], 12, v[78:79]
	v_lshl_add_u64 v[64:65], s[62:63], 0, v[64:65]
	v_ashrrev_i32_e32 v71, 31, v70
	v_lshl_add_u64 v[74:75], v[64:65], 0, v[138:139]
	v_lshlrev_b64 v[64:65], 14, v[70:71]
	v_lshl_add_u64 v[70:71], v[80:81], 0, v[64:65]
	s_waitcnt vmcnt(20)
	ds_write_b128 v231, v[202:205]
	ds_read_b128 v[202:205], v230
	s_waitcnt lgkmcnt(6)
	v_lshlrev_b32_e32 v76, 16, v194
	v_and_b32_e32 v77, 0xffff0000, v194
	v_lshlrev_b32_e32 v66, 16, v195
	v_and_b32_e32 v67, 0xffff0000, v195
	v_lshlrev_b32_e32 v78, 16, v196
	v_and_b32_e32 v79, 0xffff0000, v196
	v_lshlrev_b32_e32 v68, 16, v197
	v_and_b32_e32 v69, 0xffff0000, v197
	v_pk_add_f32 v[62:63], v[62:63], v[66:67]
	v_pk_add_f32 v[60:61], v[60:61], v[76:77]
	v_pk_add_f32 v[58:59], v[58:59], v[68:69]
	v_pk_add_f32 v[56:57], v[56:57], v[78:79]
	s_nop 0
	v_readfirstlane_b32 s98, v74
	v_readfirstlane_b32 s99, v75
	ds_write_b128 v248, v[60:63]
	ds_write_b128 v248, v[56:59] offset:16
	ds_read_b128 v[232:235], v249
	ds_read_b128 v[236:239], v249 offset:1024
	s_waitcnt lgkmcnt(6)
	global_store_dwordx4 v161, v[240:243], s[100:101] offset:512 nt
	global_store_dwordx4 v201, v[244:247], s[100:101] offset:512 nt
	s_nop 0
	v_add_u32_e32 v60, 0x90, v136
	v_lshrrev_b32_e32 v61, 3, v60
	v_lshlrev_b32_e32 v62, 6, v60
	v_lshlrev_b32_e32 v63, 2, v60
	v_and_or_b32 v61, v61, 10, s55
	v_and_or_b32 v62, v62, s48, v146
	v_and_b32_e32 v63, 32, v63
	v_lshlrev_b32_e32 v61, 10, v61
	v_bitop3_b32 v130, v62, v61, v63 bitop3:0xde
	v_lshl_add_u64 v[62:63], s[30:31], 0, v[130:131]
	v_lshl_add_u64 v[66:67], v[62:63], 0, v[72:73]
	v_ashrrev_i32_e32 v61, 31, v60
	s_waitcnt vmcnt(21)
	ds_write_b128 v231, v[206:209]
	ds_read_b128 v[206:209], v230
	s_waitcnt lgkmcnt(6)
	v_lshlrev_b32_e32 v68, 16, v202
	v_and_b32_e32 v69, 0xffff0000, v202
	v_lshlrev_b32_e32 v56, 16, v203
	v_and_b32_e32 v57, 0xffff0000, v203
	v_lshlrev_b32_e32 v70, 16, v204
	v_and_b32_e32 v71, 0xffff0000, v204
	v_lshlrev_b32_e32 v58, 16, v205
	v_and_b32_e32 v59, 0xffff0000, v205
	v_pk_add_f32 v[54:55], v[54:55], v[56:57]
	v_pk_add_f32 v[52:53], v[52:53], v[68:69]
	v_pk_add_f32 v[50:51], v[50:51], v[58:59]
	v_pk_add_f32 v[48:49], v[48:49], v[70:71]
	ds_write_b128 v248, v[52:55]
	ds_write_b128 v248, v[48:51] offset:16
	ds_read_b128 v[240:243], v249
	ds_read_b128 v[244:247], v249 offset:1024
	s_waitcnt lgkmcnt(6)
	global_store_dwordx4 v161, v[232:235], s[98:99] nt
	global_store_dwordx4 v201, v[236:239], s[98:99] nt
	s_nop 0
	v_lshlrev_b64 v[52:53], 12, v[60:61]
	v_lshl_add_u64 v[52:53], s[62:63], 0, v[52:53]
	v_lshl_add_u64 v[52:53], v[52:53], 0, v[138:139]
	v_lshl_add_u64 v[54:55], v[62:63], 0, v[64:65]
	s_waitcnt vmcnt(22)
	ds_write_b128 v231, v[210:213]
	ds_read_b128 v[210:213], v230
	s_waitcnt lgkmcnt(6)
	v_lshlrev_b32_e32 v56, 16, v206
	v_and_b32_e32 v57, 0xffff0000, v206
	v_lshlrev_b32_e32 v48, 16, v207
	v_and_b32_e32 v49, 0xffff0000, v207
	v_lshlrev_b32_e32 v58, 16, v208
	v_and_b32_e32 v59, 0xffff0000, v208
	v_lshlrev_b32_e32 v50, 16, v209
	v_and_b32_e32 v51, 0xffff0000, v209
	v_pk_add_f32 v[46:47], v[46:47], v[48:49]
	v_pk_add_f32 v[44:45], v[44:45], v[56:57]
	v_pk_add_f32 v[42:43], v[42:43], v[50:51]
	v_pk_add_f32 v[40:41], v[40:41], v[58:59]
	s_nop 0
	v_readfirstlane_b32 s100, v52
	v_readfirstlane_b32 s101, v53
	ds_write_b128 v248, v[44:47]
	ds_write_b128 v248, v[40:43] offset:16
	ds_read_b128 v[232:235], v249
	ds_read_b128 v[236:239], v249 offset:1024
	s_waitcnt lgkmcnt(6)
; __host__ __device__ __forceinline__ size_t img_off(int row, int col, int nkt) { return ((size_t)((row >> 7) * nkt + (col >> 6)) << 14) + (size_t)lds_byte(row & 127, col & 63); }
;     __device__ __forceinline__ void operator()(const f32x4 (&acc)[2][2][4][2], const Unit& u, int wr, int wc, int fr, int fq) const {
;     ...
;                 for (int bj = 0; bj < 2; ++bj) { const u32x4 xb = __builtin_nontemporal_load((const u32x4*)(x1b + img_off(row, col0 + bj * HALF, 16))); float* p = y + off + bj * HALF;
;                     const f32x4 x0 = (f32x4){__builtin_bit_cast(float, xb.x << 16), __builtin_bit_cast(float, xb.x & 0xffff0000u), __builtin_bit_cast(float, xb.y << 16), __builtin_bit_cast(float, xb.y & 0xffff0000u)};
;                     const f32x4 x1 = (f32x4){__builtin_bit_cast(float, xb.z << 16), __builtin_bit_cast(float, xb.z & 0xffff0000u), __builtin_bit_cast(float, xb.w << 16), __builtin_bit_cast(float, xb.w & 0xffff0000u)};
;                     __builtin_nontemporal_store(acc[ai][bj][m][0] + x0, (f32x4*)p); __builtin_nontemporal_store(acc[ai][bj][m][1] + x1, (f32x4*)(p + 4)); } }
	global_store_dwordx4 v161, v[240:243], s[98:99] offset:512 nt
	global_store_dwordx4 v201, v[244:247], s[98:99] offset:512 nt
	s_nop 0
	v_add_u32_e32 v44, 0xa0, v136
	v_lshrrev_b32_e32 v45, 3, v44
	v_lshlrev_b32_e32 v46, 6, v44
	v_lshlrev_b32_e32 v47, 2, v44
	v_and_or_b32 v45, v45, 12, s55
	v_and_or_b32 v46, v46, s48, v146
	v_and_b32_e32 v47, 32, v47
	v_lshlrev_b32_e32 v45, 10, v45
	v_bitop3_b32 v130, v46, v45, v47 bitop3:0xde
	v_lshl_add_u64 v[46:47], s[30:31], 0, v[130:131]
	v_lshl_add_u64 v[48:49], v[46:47], 0, v[72:73]
	v_ashrrev_i32_e32 v45, 31, v44
	s_waitcnt vmcnt(23)
	ds_write_b128 v231, v[214:217]
	ds_read_b128 v[214:217], v230
	s_waitcnt lgkmcnt(6)
	v_lshlrev_b32_e32 v50, 16, v210
	v_and_b32_e32 v51, 0xffff0000, v210
	v_lshlrev_b32_e32 v40, 16, v211
	v_and_b32_e32 v41, 0xffff0000, v211
	v_lshlrev_b32_e32 v54, 16, v212
	v_and_b32_e32 v55, 0xffff0000, v212
	v_lshlrev_b32_e32 v42, 16, v213
	v_and_b32_e32 v43, 0xffff0000, v213
	v_pk_add_f32 v[38:39], v[38:39], v[40:41]
	v_pk_add_f32 v[36:37], v[36:37], v[50:51]
	v_pk_add_f32 v[34:35], v[34:35], v[42:43]
	v_pk_add_f32 v[32:33], v[32:33], v[54:55]
	ds_write_b128 v248, v[36:39]
	ds_write_b128 v248, v[32:35] offset:16
	ds_read_b128 v[240:243], v249
	ds_read_b128 v[244:247], v249 offset:1024
	s_waitcnt lgkmcnt(6)
	global_store_dwordx4 v161, v[232:235], s[100:101] nt
	global_store_dwordx4 v201, v[236:239], s[100:101] nt
	s_nop 0
	v_lshlrev_b64 v[36:37], 12, v[44:45]
	v_lshl_add_u64 v[36:37], s[62:63], 0, v[36:37]
	v_lshl_add_u64 v[36:37], v[36:37], 0, v[138:139]
	v_lshl_add_u64 v[38:39], v[46:47], 0, v[64:65]
	s_waitcnt vmcnt(24)
	ds_write_b128 v231, v[218:221]
	ds_read_b128 v[218:221], v230
	s_waitcnt lgkmcnt(6)
	v_lshlrev_b32_e32 v40, 16, v214
	v_and_b32_e32 v41, 0xffff0000, v214
	v_lshlrev_b32_e32 v32, 16, v215
	v_and_b32_e32 v33, 0xffff0000, v215
	v_lshlrev_b32_e32 v42, 16, v216
	v_and_b32_e32 v43, 0xffff0000, v216
	v_lshlrev_b32_e32 v34, 16, v217
	v_and_b32_e32 v35, 0xffff0000, v217
	v_pk_add_f32 v[30:31], v[30:31], v[32:33]
	v_pk_add_f32 v[28:29], v[28:29], v[40:41]
	v_pk_add_f32 v[26:27], v[26:27], v[34:35]
	v_pk_add_f32 v[24:25], v[24:25], v[42:43]
	s_nop 0
	v_readfirstlane_b32 s98, v36
	v_readfirstlane_b32 s99, v37
	ds_write_b128 v248, v[28:31]
	ds_write_b128 v248, v[24:27] offset:16
	ds_read_b128 v[232:235], v249
	ds_read_b128 v[236:239], v249 offset:1024
	s_waitcnt lgkmcnt(6)
	global_store_dwordx4 v161, v[240:243], s[100:101] offset:512 nt
	global_store_dwordx4 v201, v[244:247], s[100:101] offset:512 nt
	s_nop 0
	v_add_u32_e32 v28, 0xb0, v136
	v_lshrrev_b32_e32 v29, 3, v28
	v_lshlrev_b32_e32 v30, 6, v28
	v_lshlrev_b32_e32 v31, 2, v28
	v_and_or_b32 v29, v29, 14, s55
	v_and_or_b32 v30, v30, s48, v146
	v_and_b32_e32 v31, 32, v31
	v_lshlrev_b32_e32 v29, 10, v29
	v_bitop3_b32 v130, v30, v29, v31 bitop3:0xde
	v_lshl_add_u64 v[30:31], s[30:31], 0, v[130:131]
	v_lshl_add_u64 v[32:33], v[30:31], 0, v[72:73]
	v_ashrrev_i32_e32 v29, 31, v28
	s_waitcnt vmcnt(25)
	ds_write_b128 v231, v[222:225]
	ds_read_b128 v[222:225], v230
	s_waitcnt lgkmcnt(6)
	v_lshlrev_b32_e32 v34, 16, v218
	v_and_b32_e32 v35, 0xffff0000, v218
	v_lshlrev_b32_e32 v24, 16, v219
	v_and_b32_e32 v25, 0xffff0000, v219
	v_lshlrev_b32_e32 v38, 16, v220
	v_and_b32_e32 v39, 0xffff0000, v220
	v_lshlrev_b32_e32 v26, 16, v221
	v_and_b32_e32 v27, 0xffff0000, v221
	v_pk_add_f32 v[22:23], v[22:23], v[24:25]
	v_pk_add_f32 v[20:21], v[20:21], v[34:35]
	v_pk_add_f32 v[18:19], v[18:19], v[26:27]
	v_pk_add_f32 v[16:17], v[16:17], v[38:39]
	ds_write_b128 v248, v[20:23]
	ds_write_b128 v248, v[16:19] offset:16
	ds_read_b128 v[240:243], v249
	ds_read_b128 v[244:247], v249 offset:1024
	s_waitcnt lgkmcnt(6)
	global_store_dwordx4 v161, v[232:235], s[98:99] nt
	global_store_dwordx4 v201, v[236:239], s[98:99] nt
	s_nop 0
	v_lshlrev_b64 v[20:21], 12, v[28:29]
	v_lshl_add_u64 v[20:21], s[62:63], 0, v[20:21]
	v_lshl_add_u64 v[20:21], v[20:21], 0, v[138:139]
	v_lshl_add_u64 v[22:23], v[30:31], 0, v[64:65]
	s_waitcnt vmcnt(26)
	ds_write_b128 v231, v[226:229]
	ds_read_b128 v[226:229], v230
	s_waitcnt lgkmcnt(6)
	v_lshlrev_b32_e32 v24, 16, v222
	v_and_b32_e32 v25, 0xffff0000, v222
	v_lshlrev_b32_e32 v16, 16, v223
	v_and_b32_e32 v17, 0xffff0000, v223
	v_lshlrev_b32_e32 v26, 16, v224
	v_and_b32_e32 v27, 0xffff0000, v224
	v_lshlrev_b32_e32 v18, 16, v225
	v_and_b32_e32 v19, 0xffff0000, v225
	v_pk_add_f32 v[14:15], v[14:15], v[16:17]
	v_pk_add_f32 v[12:13], v[12:13], v[24:25]
	v_pk_add_f32 v[10:11], v[10:11], v[18:19]
	v_pk_add_f32 v[8:9], v[8:9], v[26:27]
	s_nop 0
	v_readfirstlane_b32 s100, v20
	v_readfirstlane_b32 s101, v21
	ds_write_b128 v248, v[12:15]
	ds_write_b128 v248, v[8:11] offset:16
	ds_read_b128 v[232:235], v249
	ds_read_b128 v[236:239], v249 offset:1024
	s_waitcnt lgkmcnt(6)
	global_store_dwordx4 v161, v[240:243], s[98:99] offset:512 nt
	global_store_dwordx4 v201, v[244:247], s[98:99] offset:512 nt
	s_nop 0
	s_waitcnt lgkmcnt(4)
	v_lshlrev_b32_e32 v12, 16, v226
	v_and_b32_e32 v13, 0xffff0000, v226
	v_lshlrev_b32_e32 v8, 16, v227
	v_and_b32_e32 v9, 0xffff0000, v227
	v_lshlrev_b32_e32 v14, 16, v228
	v_and_b32_e32 v15, 0xffff0000, v228
	v_lshlrev_b32_e32 v10, 16, v229
	v_and_b32_e32 v11, 0xffff0000, v229
	v_pk_add_f32 v[6:7], v[6:7], v[8:9]
	v_pk_add_f32 v[4:5], v[4:5], v[12:13]
	v_pk_add_f32 v[2:3], v[2:3], v[10:11]
	v_pk_add_f32 v[0:1], v[0:1], v[14:15]
	ds_write_b128 v248, v[4:7]
	ds_write_b128 v248, v[0:3] offset:16
	ds_read_b128 v[240:243], v249
	ds_read_b128 v[244:247], v249 offset:1024
	s_waitcnt lgkmcnt(4)
	global_store_dwordx4 v161, v[232:235], s[100:101] nt
	global_store_dwordx4 v201, v[236:239], s[100:101] nt
	s_waitcnt lgkmcnt(0)
	global_store_dwordx4 v161, v[240:243], s[100:101] offset:512 nt
	global_store_dwordx4 v201, v[244:247], s[100:101] offset:512 nt
	s_cbranch_vccnz .LBB0_1412
	s_andn2_b64 vcc, exec, s[18:19]
	s_cbranch_vccnz .LBB0_1411
	s_barrier
	s_branch .LBB0_1411
